# E60: E52 plus MLA QK segment opens with MFMAs only: its head VALU block (row-sum adds, exp2, cvt) re-spaced two per gap behind MFMA 8..22
# speedup vs baseline: 1.0013x; 1.0013x over previous
; #define PK4(P, BASE, OUT) do { u32x4 w = {cvtb(P[BASE + 0], P[BASE + 1]), cvtb(P[BASE + 2], P[BASE + 3]), \
;     cvtb(P[BASE + 4], P[BASE + 5]), cvtb(P[BASE + 6], P[BASE + 7])}; OUT = *reinterpret_cast<bf16x8*>(&w); } while (0)
; __device__ __forceinline__ void finishSM(f32x16& p0, f32x16& p1, float alpha, float& l_reg, bf16x8& pa0, bf16x8& pa1, bf16x8& pa2, bf16x8& pa3) {
; #pragma unroll
;   for (int r = 0; r < 16; ++r) p1[r] = __builtin_amdgcn_exp2f(p1[r]);
;   float ps = 0;
; #pragma unroll
;   for (int r = 0; r < 16; ++r) ps += p0[r];
; #pragma unroll
;   for (int r = 0; r < 16; ++r) ps += p1[r];
;   { auto rr = __builtin_amdgcn_permlane32_swap(__float_as_uint(ps), __float_as_uint(ps), false, false);
;     ps = __uint_as_float(rr[0]) + __uint_as_float(rr[1]); }
;   l_reg = l_reg * alpha + ps;
;     ...
;   PK4(p0, 0, pa0); PK4(p0, 8, pa1); PK4(p1, 0, pa2); PK4(p1, 8, pa3);
;     ...
; }
; template <int NQK>
; __device__ __forceinline__ void qkt(f32x16& p0, f32x16& p1, const char* Ks, const bf16x8* qr, int r32, int hi) {
;   constexpr int KROW = NQK * 32 + 16;
;   p0 = f32x16{}; p1 = f32x16{};
; #pragma unroll
;   for (int d0 = 0; d0 < NQK; ++d0) { const int cb = (d0 * 16 + hi * 8) * 2;
;     bf16x8 b0 = *reinterpret_cast<const bf16x8*>(Ks + r32 * KROW + cb);
;     bf16x8 b1 = *reinterpret_cast<const bf16x8*>(Ks + (32 + r32) * KROW + cb);
;     p0 = __builtin_amdgcn_mfma_f32_32x32x16_bf16(b0, qr[d0], p0, 0, 0, 0);
;     p1 = __builtin_amdgcn_mfma_f32_32x32x16_bf16(b1, qr[d0], p1, 0, 0, 0); }
; }
.LBB0_2539:
	s_mov_b32 s14, s44
	s_mov_b32 s44, s8
	s_mul_i32 s8, s14, 0x6400
	v_add_u32_e32 v169, s8, v174
	ds_read_b128 v[64:67], v169 offset:61952
	ds_read_b128 v[68:71], v169 offset:49152
	ds_read_b128 v[180:183], v169 offset:49184
	ds_read_b128 v[222:225], v169 offset:61984
	s_waitcnt lgkmcnt(2)
	v_mfma_f32_32x32x16_bf16 v[80:95], v[68:71], v[140:143], 0
	v_mfma_f32_32x32x16_bf16 v[64:79], v[64:67], v[140:143], 0
	s_waitcnt lgkmcnt(1)
	v_mfma_f32_32x32x16_bf16 v[80:95], v[180:183], v[136:139], v[80:95]
	s_waitcnt lgkmcnt(0)
	v_mfma_f32_32x32x16_bf16 v[64:79], v[222:225], v[136:139], v[64:79]
	ds_read_b128 v[180:183], v169 offset:49216
	ds_read_b128 v[222:225], v169 offset:62016
	s_waitcnt lgkmcnt(1)
	v_mfma_f32_32x32x16_bf16 v[80:95], v[180:183], v[132:135], v[80:95]
	s_waitcnt lgkmcnt(0)
	v_mfma_f32_32x32x16_bf16 v[64:79], v[222:225], v[132:135], v[64:79]
	ds_read_b128 v[180:183], v169 offset:49248
	ds_read_b128 v[222:225], v169 offset:62048
	s_waitcnt lgkmcnt(1)
	v_mfma_f32_32x32x16_bf16 v[80:95], v[180:183], v[128:131], v[80:95]
	s_waitcnt lgkmcnt(0)
	v_mfma_f32_32x32x16_bf16 v[64:79], v[222:225], v[128:131], v[64:79]
	ds_read_b128 v[180:183], v169 offset:49280
	ds_read_b128 v[222:225], v169 offset:62080
	s_waitcnt lgkmcnt(1)
	v_mfma_f32_32x32x16_bf16 v[80:95], v[180:183], v[124:127], v[80:95]
	v_exp_f32_e32 v231, v146
	v_add_f32_e32 v146, 0, v184
	s_waitcnt lgkmcnt(0)
	v_mfma_f32_32x32x16_bf16 v[64:79], v[222:225], v[124:127], v[64:79]
	v_add_f32_e32 v146, v185, v146
	v_add_f32_e32 v146, v189, v146
	ds_read_b128 v[180:183], v169 offset:49312
	ds_read_b128 v[222:225], v169 offset:62112
	s_waitcnt lgkmcnt(1)
	v_mfma_f32_32x32x16_bf16 v[80:95], v[180:183], v[120:123], v[80:95]
	v_add_f32_e32 v146, v191, v146
	v_add_f32_e32 v146, v198, v146
	s_waitcnt lgkmcnt(0)
	v_mfma_f32_32x32x16_bf16 v[64:79], v[222:225], v[120:123], v[64:79]
	v_add_f32_e32 v146, v200, v146
	v_add_f32_e32 v146, v214, v146
	ds_read_b128 v[180:183], v169 offset:49344
	ds_read_b128 v[222:225], v169 offset:62144
	s_waitcnt lgkmcnt(1)
	v_mfma_f32_32x32x16_bf16 v[80:95], v[180:183], v[116:119], v[80:95]
	v_add_f32_e32 v146, v217, v146
	v_add_f32_e32 v146, v215, v146
	s_waitcnt lgkmcnt(0)
	v_mfma_f32_32x32x16_bf16 v[64:79], v[222:225], v[116:119], v[64:79]
	v_add_f32_e32 v146, v218, v146
	v_add_f32_e32 v146, v199, v146
	ds_read_b128 v[180:183], v169 offset:49376
	ds_read_b128 v[222:225], v169 offset:62176
	s_waitcnt lgkmcnt(1)
	v_mfma_f32_32x32x16_bf16 v[80:95], v[180:183], v[112:115], v[80:95]
	v_add_f32_e32 v146, v201, v146
	v_add_f32_e32 v146, v216, v146
	s_waitcnt lgkmcnt(0)
	v_mfma_f32_32x32x16_bf16 v[64:79], v[222:225], v[112:115], v[64:79]
	v_add_f32_e32 v146, v219, v146
	v_add_f32_e32 v146, v220, v146
	ds_read_b128 v[180:183], v169 offset:49408
	ds_read_b128 v[222:225], v169 offset:62208
	s_waitcnt lgkmcnt(1)
	v_mfma_f32_32x32x16_bf16 v[80:95], v[180:183], v[108:111], v[80:95]
	v_add_f32_e32 v146, v221, v146
	v_exp_f32_e32 v229, v150
	s_waitcnt lgkmcnt(0)
	v_mfma_f32_32x32x16_bf16 v[64:79], v[222:225], v[108:111], v[64:79]
	v_exp_f32_e32 v226, v155
	v_exp_f32_e32 v227, v152
	ds_read_b128 v[180:183], v169 offset:49440
	ds_read_b128 v[222:225], v169 offset:62240
	s_waitcnt lgkmcnt(1)
	v_mfma_f32_32x32x16_bf16 v[80:95], v[180:183], v[104:107], v[80:95]
	v_exp_f32_e32 v228, v153
	v_exp_f32_e32 v230, v151
	s_waitcnt lgkmcnt(0)
	v_mfma_f32_32x32x16_bf16 v[64:79], v[222:225], v[104:107], v[64:79]
	v_exp_f32_e32 v148, v148
	v_exp_f32_e32 v149, v149
	ds_read_b128 v[180:183], v169 offset:49472
	ds_read_b128 v[222:225], v169 offset:62272
	s_waitcnt lgkmcnt(1)
	v_mfma_f32_32x32x16_bf16 v[80:95], v[180:183], v[100:103], v[80:95]
	v_exp_f32_e32 v232, v147
	v_cvt_pk_bf16_f32 v155, v199, v201
	s_waitcnt lgkmcnt(0)
	v_mfma_f32_32x32x16_bf16 v[64:79], v[222:225], v[100:103], v[64:79]
	v_cvt_pk_bf16_f32 v147, v229, v230
	ds_read_b128 v[180:183], v169 offset:49504
	ds_read_b128 v[222:225], v169 offset:62304
	v_exp_f32_e32 v169, v160
	v_cvt_pk_bf16_f32 v160, v198, v200
	v_add_f32_e32 v146, v169, v146
	s_waitcnt lgkmcnt(1)
	v_mfma_f32_32x32x16_bf16 v[80:95], v[180:183], v[96:99], v[80:95]
	v_exp_f32_e32 v180, v161
	v_exp_f32_e32 v183, v158
	v_cvt_pk_bf16_f32 v158, v184, v185
	v_cvt_pk_bf16_f32 v161, v214, v217
	v_add_f32_e32 v146, v180, v146
	v_cvt_pk_bf16_f32 v150, v169, v180
	v_add_f32_e32 v146, v183, v146
	s_nop 4
	v_max_f32_e32 v169, v81, v81
	v_max_f32_e32 v180, v80, v80
	s_waitcnt lgkmcnt(0)
; #define SBAR() __builtin_amdgcn_sched_barrier(0)
; __device__ __forceinline__ void decideSM(const f32x16& p0, const f32x16& p1, float& m_reg, float& mn, float& alpha, const float C, const float thr) {
;   float pmax = p0[0];
; #pragma unroll
;   for (int r = 1; r < 16; ++r) pmax = fmaxf(pmax, p0[r]);
; #pragma unroll
;   for (int r = 0; r < 16; ++r) pmax = fmaxf(pmax, p1[r]);
;   { auto rr = __builtin_amdgcn_permlane32_swap(__float_as_uint(pmax), __float_as_uint(pmax), false, false);
;     pmax = fmaxf(__uint_as_float(rr[0]), __uint_as_float(rr[1])); }
;   if (__builtin_expect(__all(pmax - m_reg <= thr), 1)) { mn = m_reg; alpha = 1.f; }
;   else { mn = fmaxf(m_reg, pmax); alpha = __builtin_amdgcn_exp2f((m_reg - mn) * C); m_reg = mn; }
; }
; __device__ __forceinline__ void finishSM(f32x16& p0, f32x16& p1, float alpha, float& l_reg, bf16x8& pa0, bf16x8& pa1, bf16x8& pa2, bf16x8& pa3) {
; #pragma unroll
;   for (int r = 0; r < 16; ++r) p1[r] = __builtin_amdgcn_exp2f(p1[r]);
;   float ps = 0;
; #pragma unroll
;   for (int r = 0; r < 16; ++r) ps += p0[r];
; #pragma unroll
;   for (int r = 0; r < 16; ++r) ps += p1[r];
;   { auto rr = __builtin_amdgcn_permlane32_swap(__float_as_uint(ps), __float_as_uint(ps), false, false);
;     ps = __uint_as_float(rr[0]) + __uint_as_float(rr[1]); }
;   l_reg = l_reg * alpha + ps;
;     ...
;   PK4(p0, 0, pa0); PK4(p0, 8, pa1); PK4(p1, 0, pa2); PK4(p1, 8, pa3);
;     ...
; }
; template <int D0> __device__ __forceinline__ void pv_one_sm(f32x16& od, int vb, bf16x8 pa0, bf16x8 pa1, bf16x8 pa2, bf16x8 pa3, f32x16& q0, f32x16& q1, const float C, const float mnC) {
;   const s16x4 l0 = tr_read<v_rd_off(D0, 0, 0)>(vb), h0 = tr_read<v_rd_off(D0, 0, 1)>(vb), l1 = tr_read<v_rd_off(D0, 1, 0)>(vb), h1 = tr_read<v_rd_off(D0, 1, 1)>(vb);
;   const s16x4 l2 = tr_read<v_rd_off(D0, 2, 0)>(vb), h2 = tr_read<v_rd_off(D0, 2, 1)>(vb), l3 = tr_read<v_rd_off(D0, 3, 0)>(vb), h3 = tr_read<v_rd_off(D0, 3, 1)>(vb);
;   asm volatile("s_waitcnt lgkmcnt(0)" ::: "memory"); SBAR();
;     ...
;   od = __builtin_amdgcn_mfma_f32_32x32x16_bf16(pa0, PK(l0, h0), od, 0, 0, 0);
;   od = __builtin_amdgcn_mfma_f32_32x32x16_bf16(pa1, PK(l1, h1), od, 0, 0, 0);
;   od = __builtin_amdgcn_mfma_f32_32x32x16_bf16(pa2, PK(l2, h2), od, 0, 0, 0);
;   od = __builtin_amdgcn_mfma_f32_32x32x16_bf16(pa3, PK(l3, h3), od, 0, 0, 0);
	v_mfma_f32_32x32x16_bf16 v[64:79], v[222:225], v[96:99], v[64:79]
	v_max_f32_e32 v169, v180, v169
	v_max3_f32 v169, v169, v82, v83
	v_max3_f32 v169, v169, v84, v85
	v_max3_f32 v169, v169, v86, v87
	v_max3_f32 v169, v169, v88, v89
	v_max3_f32 v169, v169, v90, v91
	v_exp_f32_e32 v222, v159
	v_max3_f32 v169, v169, v92, v93
	v_exp_f32_e32 v223, v156
	v_max3_f32 v169, v169, v94, v95
	v_exp_f32_e32 v224, v157
	s_nop 0
	v_max3_f32 v169, v169, v64, v65
	v_exp_f32_e32 v225, v154
	v_max3_f32 v169, v169, v66, v67
	v_add_f32_e32 v146, v222, v146
	v_max3_f32 v169, v169, v68, v69
	v_add_f32_e32 v146, v223, v146
	v_max3_f32 v169, v169, v70, v71
	v_add_f32_e32 v146, v224, v146
	v_max3_f32 v169, v169, v72, v73
	v_add_f32_e32 v146, v225, v146
	v_max3_f32 v169, v169, v74, v75
	v_add_f32_e32 v146, v226, v146
	v_max3_f32 v169, v169, v76, v77
	v_add_f32_e32 v146, v227, v146
	v_max3_f32 v169, v169, v78, v79
	v_add_f32_e32 v146, v228, v146
	v_mov_b32_e32 v180, v169
	v_add_f32_e32 v146, v229, v146
	s_nop 0
	v_permlane32_swap_b32_e32 v169, v180
	v_add_f32_e32 v146, v230, v146
	v_max_f32_e32 v180, v180, v180
	v_max_f32_e32 v169, v169, v169
	v_add_f32_e32 v146, v148, v146
	v_max_f32_e32 v169, v169, v180
	v_add_f32_e32 v146, v149, v146
	v_sub_f32_e32 v180, v169, v178
	v_add_f32_e32 v146, v231, v146
	v_cmp_ge_f32_e32 vcc, s56, v180
	v_max_f32_e32 v180, v178, v178
	v_add_f32_e32 v181, v232, v146
	v_max_f32_e32 v180, v180, v169
	v_mov_b32_e32 v182, v181
	s_cmp_eq_u64 vcc, exec
	v_sub_f32_e32 v169, v178, v180
	v_permlane32_swap_b32_e32 v181, v182
	s_cselect_b64 s[8:9], -1, 0
	v_mul_f32_e32 v169, 0x3dd53b94, v169
	v_cvt_pk_bf16_f32 v159, v189, v191
	v_cvt_pk_bf16_f32 v154, v215, v218
	v_cvt_pk_bf16_f32 v156, v216, v219
	v_cvt_pk_bf16_f32 v157, v220, v221
	v_cvt_pk_bf16_f32 v151, v183, v222
	v_cvt_pk_bf16_f32 v152, v223, v224
	v_cvt_pk_bf16_f32 v153, v225, v226
	v_cvt_pk_bf16_f32 v146, v227, v228
	v_cvt_pk_bf16_f32 v148, v148, v149
	v_cvt_pk_bf16_f32 v149, v231, v232
	s_add_i32 s10, s13, 0xfffe8000
	s_mov_b32 s38, s30
	s_mov_b32 s39, s31
	s_add_i32 s11, s13, 0xffff0000
	buffer_load_dwordx4 v[198:201], v170, s[28:31], s10 offen
	buffer_load_dwordx4 v[214:217], v170, s[28:31], s11 offen
	buffer_load_dwordx4 v[218:221], v171, s[36:39], s12 offen
	buffer_load_dwordx4 v[222:225], v176, s[36:39], s12 offen
	buffer_load_dwordx4 v[226:229], v177, s[36:39], s12 offen
	v_exp_f32_e32 v183, v169
	s_lshl_b32 s16, s44, 14
	v_add_u32_e32 v169, s16, v168
	ds_read_b64_tr_b16 v[230:231], v169 offset:0
	ds_read_b64_tr_b16 v[232:233], v169 offset:0x800
	ds_read_b64_tr_b16 v[234:235], v169 offset:0x1000
	ds_read_b64_tr_b16 v[236:237], v169 offset:0x1800
	ds_read_b64_tr_b16 v[238:239], v169 offset:0x2000
	ds_read_b64_tr_b16 v[240:241], v169 offset:0x2800
	ds_read_b64_tr_b16 v[242:243], v169 offset:0x3000
	ds_read_b64_tr_b16 v[244:245], v169 offset:0x3800
	s_waitcnt lgkmcnt(6)
	s_nop 0
	v_mfma_f32_32x32x16_bf16 v[0:15], v[158:161], v[230:233], v[0:15]
	ds_read_b64_tr_b16 v[230:231], v169 offset:0x200
	ds_read_b64_tr_b16 v[232:233], v169 offset:0xa00
	s_waitcnt lgkmcnt(6)
	v_mfma_f32_32x32x16_bf16 v[0:15], v[154:157], v[234:237], v[0:15]
	ds_read_b64_tr_b16 v[234:235], v169 offset:0x1200
	ds_read_b64_tr_b16 v[236:237], v169 offset:0x1a00
	s_waitcnt lgkmcnt(6)
	v_mfma_f32_32x32x16_bf16 v[0:15], v[150:153], v[238:241], v[0:15]
	ds_read_b64_tr_b16 v[238:239], v169 offset:0x2200
	ds_read_b64_tr_b16 v[240:241], v169 offset:0x2a00
	s_waitcnt lgkmcnt(6)
	v_mfma_f32_32x32x16_bf16 v[0:15], v[146:149], v[242:245], v[0:15]
	ds_read_b64_tr_b16 v[242:243], v169 offset:0x3200
	ds_read_b64_tr_b16 v[244:245], v169 offset:0x3a00
	s_waitcnt lgkmcnt(6)
	v_mfma_f32_32x32x16_bf16 v[48:63], v[158:161], v[230:233], v[48:63]
	ds_read_b64_tr_b16 v[230:231], v169 offset:0x400
	ds_read_b64_tr_b16 v[232:233], v169 offset:0xc00
	s_waitcnt lgkmcnt(6)
	v_mfma_f32_32x32x16_bf16 v[48:63], v[154:157], v[234:237], v[48:63]
	ds_read_b64_tr_b16 v[234:235], v169 offset:0x1400
	ds_read_b64_tr_b16 v[236:237], v169 offset:0x1c00
	s_waitcnt lgkmcnt(6)
	v_mfma_f32_32x32x16_bf16 v[48:63], v[150:153], v[238:241], v[48:63]
	ds_read_b64_tr_b16 v[238:239], v169 offset:0x2400
	ds_read_b64_tr_b16 v[240:241], v169 offset:0x2c00
	s_waitcnt lgkmcnt(6)
	v_mfma_f32_32x32x16_bf16 v[48:63], v[146:149], v[242:245], v[48:63]
	ds_read_b64_tr_b16 v[242:243], v169 offset:0x3400
	ds_read_b64_tr_b16 v[244:245], v169 offset:0x3c00
	s_waitcnt lgkmcnt(6)
	v_mfma_f32_32x32x16_bf16 v[32:47], v[158:161], v[230:233], v[32:47]
	ds_read_b64_tr_b16 v[230:231], v169 offset:0x600
	ds_read_b64_tr_b16 v[232:233], v169 offset:0xe00
	s_waitcnt lgkmcnt(6)
	v_mfma_f32_32x32x16_bf16 v[32:47], v[154:157], v[234:237], v[32:47]
	ds_read_b64_tr_b16 v[234:235], v169 offset:0x1600
	ds_read_b64_tr_b16 v[236:237], v169 offset:0x1e00
	s_waitcnt lgkmcnt(6)
	v_mfma_f32_32x32x16_bf16 v[32:47], v[150:153], v[238:241], v[32:47]
	ds_read_b64_tr_b16 v[238:239], v169 offset:0x2600
	ds_read_b64_tr_b16 v[240:241], v169 offset:0x2e00
	s_waitcnt lgkmcnt(6)
	v_mfma_f32_32x32x16_bf16 v[32:47], v[146:149], v[242:245], v[32:47]
	ds_read_b64_tr_b16 v[242:243], v169 offset:0x3600
	ds_read_b64_tr_b16 v[244:245], v169 offset:0x3e00
	s_waitcnt lgkmcnt(0)
	v_mfma_f32_32x32x16_bf16 v[16:31], v[158:161], v[230:233], v[16:31]
	s_waitcnt vmcnt(0)
	s_lshl_b32 s15, s51, 14
	s_mul_i32 s17, s51, 0x6400
	v_cndmask_b32_e64 v183, v183, 1.0, s[8:9]
	v_cmp_gt_f32_e32 vcc, 1.0, v183
	v_mfma_f32_32x32x16_bf16 v[16:31], v[154:157], v[234:237], v[16:31]
	v_add_u32_e32 v154, s15, v175
	s_waitcnt vmcnt(4)
	ds_write_b128 v154, v[198:201]
	s_waitcnt vmcnt(3)
	ds_write_b128 v154, v[214:217] offset:8192
	v_mfma_f32_32x32x16_bf16 v[16:31], v[150:153], v[238:241], v[16:31]
	v_add_u32_e32 v150, s17, v173
	s_waitcnt vmcnt(2)
	ds_write_b128 v150, v[218:221] offset:49152
	s_waitcnt vmcnt(1)
	ds_write_b128 v150, v[222:225] offset:49280
	s_waitcnt vmcnt(0)
	ds_write_b128 v150, v[226:229] offset:49408
	v_mfma_f32_32x32x16_bf16 v[16:31], v[146:149], v[242:245], v[16:31]
	s_cbranch_vccz .LBB0_2543
; template <int NQK>
; __device__ __forceinline__ void qkt(f32x16& p0, f32x16& p1, const char* Ks, const bf16x8* qr, int r32, int hi) {
;   constexpr int KROW = NQK * 32 + 16;
;   p0 = f32x16{}; p1 = f32x16{};
; #pragma unroll
;   for (int d0 = 0; d0 < NQK; ++d0) { const int cb = (d0 * 16 + hi * 8) * 2;
;     bf16x8 b0 = *reinterpret_cast<const bf16x8*>(Ks + r32 * KROW + cb);
;     bf16x8 b1 = *reinterpret_cast<const bf16x8*>(Ks + (32 + r32) * KROW + cb);
;     p0 = __builtin_amdgcn_mfma_f32_32x32x16_bf16(b0, qr[d0], p0, 0, 0, 0);
;     p1 = __builtin_amdgcn_mfma_f32_32x32x16_bf16(b1, qr[d0], p1, 0, 0, 0); }
; template <int D0> __device__ __forceinline__ void pv_one_sm(f32x16& od, int vb, bf16x8 pa0, bf16x8 pa1, bf16x8 pa2, bf16x8 pa3, f32x16& q0, f32x16& q1, const float C, const float mnC) {
;     ...
;   if (D0 < 2) {
; #pragma unroll
;     for (int r = 8 * D0; r < 8 * D0 + 8; ++r) q0[r] = __builtin_amdgcn_exp2f(fmaf(q0[r], C, mnC));
;   } else {
; #pragma unroll
;     for (int r = 8 * (D0 - 2); r < 8 * (D0 - 2) + 8; ++r) q1[r] = fmaf(q1[r], C, mnC);
;   }
; }
	s_and_saveexec_b64 s[10:11], s[6:7]
	ds_write_b32 v166, v183 offset:128
	s_or_b64 exec, exec, s[10:11]
	s_waitcnt lgkmcnt(0)
	v_add_u32_e32 v158, v165, v162
	ds_read_b128 v[146:149], v158 offset:224
	ds_read_b128 v[150:153], v158 offset:192
	ds_read_b128 v[154:157], v158 offset:160
	ds_read_b128 v[158:161], v158 offset:128
	s_waitcnt lgkmcnt(3)
	v_pk_mul_f32 v[12:13], v[12:13], v[146:147]
	s_waitcnt lgkmcnt(2)
	v_pk_mul_f32 v[8:9], v[8:9], v[150:151]
	s_waitcnt lgkmcnt(1)
	v_pk_mul_f32 v[4:5], v[4:5], v[154:155]
	v_pk_mul_f32 v[14:15], v[14:15], v[148:149]
	v_pk_mul_f32 v[10:11], v[10:11], v[152:153]
	v_pk_mul_f32 v[6:7], v[6:7], v[156:157]
	s_waitcnt lgkmcnt(0)
	v_pk_mul_f32 v[2:3], v[2:3], v[160:161]
	v_pk_mul_f32 v[0:1], v[0:1], v[158:159]
	v_pk_mul_f32 v[60:61], v[60:61], v[146:147]
	v_pk_mul_f32 v[56:57], v[56:57], v[150:151]
	v_pk_mul_f32 v[52:53], v[52:53], v[154:155]
	v_pk_mul_f32 v[62:63], v[62:63], v[148:149]
	v_pk_mul_f32 v[58:59], v[58:59], v[152:153]
	v_pk_mul_f32 v[54:55], v[54:55], v[156:157]
	v_pk_mul_f32 v[50:51], v[50:51], v[160:161]
	v_pk_mul_f32 v[48:49], v[48:49], v[158:159]
	v_pk_mul_f32 v[44:45], v[44:45], v[146:147]
	v_pk_mul_f32 v[40:41], v[40:41], v[150:151]
	v_pk_mul_f32 v[36:37], v[36:37], v[154:155]
	v_pk_mul_f32 v[46:47], v[46:47], v[148:149]
	v_pk_mul_f32 v[42:43], v[42:43], v[152:153]
	v_pk_mul_f32 v[38:39], v[38:39], v[156:157]
	v_pk_mul_f32 v[34:35], v[34:35], v[160:161]
	v_pk_mul_f32 v[32:33], v[32:33], v[158:159]
	v_pk_mul_f32 v[28:29], v[28:29], v[146:147]
	v_pk_mul_f32 v[24:25], v[24:25], v[150:151]
	v_pk_mul_f32 v[20:21], v[20:21], v[154:155]
	v_pk_mul_f32 v[30:31], v[30:31], v[148:149]
	v_pk_mul_f32 v[26:27], v[26:27], v[152:153]
	v_pk_mul_f32 v[22:23], v[22:23], v[156:157]
	v_pk_mul_f32 v[18:19], v[18:19], v[160:161]
	v_pk_mul_f32 v[16:17], v[16:17], v[158:159]
.LBB0_2543:
	v_cndmask_b32_e64 v178, v180, v178, s[8:9]
	v_mul_f32_e32 v154, 0xbdd53b94, v178
	v_fmamk_f32 v80, v80, 0x3dd53b94, v154
	v_exp_f32_e32 v155, v80
	v_fmamk_f32 v80, v81, 0x3dd53b94, v154
	v_exp_f32_e32 v156, v80
	v_fmamk_f32 v80, v82, 0x3dd53b94, v154
	v_exp_f32_e32 v157, v80
	v_fmamk_f32 v80, v83, 0x3dd53b94, v154
	v_exp_f32_e32 v159, v80
	v_fmamk_f32 v80, v84, 0x3dd53b94, v154
	v_exp_f32_e32 v160, v80
	v_fmamk_f32 v80, v85, 0x3dd53b94, v154
	v_exp_f32_e32 v161, v80
	v_fmamk_f32 v80, v86, 0x3dd53b94, v154
	v_exp_f32_e32 v180, v80
	v_fmamk_f32 v80, v87, 0x3dd53b94, v154
	v_exp_f32_e32 v189, v80
	v_fmamk_f32 v80, v88, 0x3dd53b94, v154
	v_exp_f32_e32 v191, v80
	v_fmamk_f32 v80, v89, 0x3dd53b94, v154
	v_exp_f32_e32 v198, v80
	v_fmamk_f32 v80, v90, 0x3dd53b94, v154
	v_exp_f32_e32 v199, v80
	v_fmamk_f32 v80, v91, 0x3dd53b94, v154
	v_exp_f32_e32 v200, v80
	v_fmamk_f32 v80, v92, 0x3dd53b94, v154
	v_exp_f32_e32 v201, v80
	v_fmamk_f32 v80, v93, 0x3dd53b94, v154
	v_exp_f32_e32 v214, v80
	v_fmamk_f32 v80, v94, 0x3dd53b94, v154
	v_exp_f32_e32 v215, v80
	v_fmamk_f32 v80, v95, 0x3dd53b94, v154
	v_fmamk_f32 v184, v66, 0x3dd53b94, v154
	v_fmamk_f32 v185, v68, 0x3dd53b94, v154
	v_exp_f32_e32 v216, v80
	v_fmamk_f32 v158, v64, 0x3dd53b94, v154
	v_fmamk_f32 v217, v70, 0x3dd53b94, v154
	v_fmamk_f32 v218, v65, 0x3dd53b94, v154
	v_fmamk_f32 v219, v67, 0x3dd53b94, v154
	v_fmamk_f32 v220, v69, 0x3dd53b94, v154
	v_fmamk_f32 v221, v71, 0x3dd53b94, v154
	v_fmamk_f32 v222, v72, 0x3dd53b94, v154
	v_fmamk_f32 v223, v73, 0x3dd53b94, v154
	v_fmamk_f32 v224, v74, 0x3dd53b94, v154
	v_fmamk_f32 v225, v75, 0x3dd53b94, v154
	v_fmamk_f32 v226, v76, 0x3dd53b94, v154
	v_fmamk_f32 v227, v77, 0x3dd53b94, v154
	v_fmamk_f32 v228, v78, 0x3dd53b94, v154
	v_fmac_f32_e32 v154, 0x3dd53b94, v79
	s_waitcnt lgkmcnt(0)
	s_barrier
	v_add_u32_e32 v229, s17, v174
	ds_read_b128 v[64:67], v229 offset:61952
	ds_read_b128 v[68:71], v229 offset:49152
	ds_read_b128 v[146:149], v229 offset:49184
	ds_read_b128 v[150:153], v229 offset:61984
	s_waitcnt lgkmcnt(2)
	v_mfma_f32_32x32x16_bf16 v[80:95], v[68:71], v[140:143], 0
	v_mfma_f32_32x32x16_bf16 v[64:79], v[64:67], v[140:143], 0
	s_waitcnt lgkmcnt(1)
	v_mfma_f32_32x32x16_bf16 v[80:95], v[146:149], v[136:139], v[80:95]
	s_waitcnt lgkmcnt(0)
	v_mfma_f32_32x32x16_bf16 v[64:79], v[150:153], v[136:139], v[64:79]
	ds_read_b128 v[146:149], v229 offset:49216
	ds_read_b128 v[150:153], v229 offset:62016
	s_waitcnt lgkmcnt(1)
	v_mfma_f32_32x32x16_bf16 v[80:95], v[146:149], v[132:135], v[80:95]
	s_waitcnt lgkmcnt(0)
	v_mfma_f32_32x32x16_bf16 v[64:79], v[150:153], v[132:135], v[64:79]
	ds_read_b128 v[146:149], v229 offset:49248
	ds_read_b128 v[150:153], v229 offset:62048
	s_waitcnt lgkmcnt(1)
	v_mfma_f32_32x32x16_bf16 v[80:95], v[146:149], v[128:131], v[80:95]
	s_waitcnt lgkmcnt(0)
	v_mfma_f32_32x32x16_bf16 v[64:79], v[150:153], v[128:131], v[64:79]
	ds_read_b128 v[146:149], v229 offset:49280
	ds_read_b128 v[150:153], v229 offset:62080
	s_waitcnt lgkmcnt(1)
	v_mfma_f32_32x32x16_bf16 v[80:95], v[146:149], v[124:127], v[80:95]
	v_exp_f32_e32 v217, v217
	s_waitcnt lgkmcnt(0)
	v_mfma_f32_32x32x16_bf16 v[64:79], v[150:153], v[124:127], v[64:79]
	ds_read_b128 v[146:149], v229 offset:49312
	ds_read_b128 v[150:153], v229 offset:62112
	s_waitcnt lgkmcnt(1)
	v_mfma_f32_32x32x16_bf16 v[80:95], v[146:149], v[120:123], v[80:95]
	s_waitcnt lgkmcnt(0)
	v_mfma_f32_32x32x16_bf16 v[64:79], v[150:153], v[120:123], v[64:79]
	ds_read_b128 v[146:149], v229 offset:49344
	ds_read_b128 v[150:153], v229 offset:62144
	s_waitcnt lgkmcnt(1)
	v_mfma_f32_32x32x16_bf16 v[80:95], v[146:149], v[116:119], v[80:95]
	s_waitcnt lgkmcnt(0)
	v_mfma_f32_32x32x16_bf16 v[64:79], v[150:153], v[116:119], v[64:79]
	ds_read_b128 v[146:149], v229 offset:49376
	ds_read_b128 v[150:153], v229 offset:62176
	s_waitcnt lgkmcnt(1)
; #define PK4(P, BASE, OUT) do { u32x4 w = {cvtb(P[BASE + 0], P[BASE + 1]), cvtb(P[BASE + 2], P[BASE + 3]), \
;     cvtb(P[BASE + 4], P[BASE + 5]), cvtb(P[BASE + 6], P[BASE + 7])}; OUT = *reinterpret_cast<bf16x8*>(&w); } while (0)
; __device__ __forceinline__ void decideSM(const f32x16& p0, const f32x16& p1, float& m_reg, float& mn, float& alpha, const float C, const float thr) {
;   float pmax = p0[0];
; #pragma unroll
;   for (int r = 1; r < 16; ++r) pmax = fmaxf(pmax, p0[r]);
; #pragma unroll
;   for (int r = 0; r < 16; ++r) pmax = fmaxf(pmax, p1[r]);
;   { auto rr = __builtin_amdgcn_permlane32_swap(__float_as_uint(pmax), __float_as_uint(pmax), false, false);
;     pmax = fmaxf(__uint_as_float(rr[0]), __uint_as_float(rr[1])); }
;   if (__builtin_expect(__all(pmax - m_reg <= thr), 1)) { mn = m_reg; alpha = 1.f; }
;   else { mn = fmaxf(m_reg, pmax); alpha = __builtin_amdgcn_exp2f((m_reg - mn) * C); m_reg = mn; }
; }
; __device__ __forceinline__ void finishSM(f32x16& p0, f32x16& p1, float alpha, float& l_reg, bf16x8& pa0, bf16x8& pa1, bf16x8& pa2, bf16x8& pa3) {
; #pragma unroll
;   for (int r = 0; r < 16; ++r) p1[r] = __builtin_amdgcn_exp2f(p1[r]);
;   float ps = 0;
; #pragma unroll
;   for (int r = 0; r < 16; ++r) ps += p0[r];
; #pragma unroll
;   for (int r = 0; r < 16; ++r) ps += p1[r];
;   { auto rr = __builtin_amdgcn_permlane32_swap(__float_as_uint(ps), __float_as_uint(ps), false, false);
;     ps = __uint_as_float(rr[0]) + __uint_as_float(rr[1]); }
;   l_reg = l_reg * alpha + ps;
;     ...
;   PK4(p0, 0, pa0); PK4(p0, 8, pa1); PK4(p1, 0, pa2); PK4(p1, 8, pa3);
;     ...
; }
; template <int NQK>
; __device__ __forceinline__ void qkt(f32x16& p0, f32x16& p1, const char* Ks, const bf16x8* qr, int r32, int hi) {
;   constexpr int KROW = NQK * 32 + 16;
;   p0 = f32x16{}; p1 = f32x16{};
; #pragma unroll
;   for (int d0 = 0; d0 < NQK; ++d0) { const int cb = (d0 * 16 + hi * 8) * 2;
;     bf16x8 b0 = *reinterpret_cast<const bf16x8*>(Ks + r32 * KROW + cb);
;     bf16x8 b1 = *reinterpret_cast<const bf16x8*>(Ks + (32 + r32) * KROW + cb);
;     p0 = __builtin_amdgcn_mfma_f32_32x32x16_bf16(b0, qr[d0], p0, 0, 0, 0);
;     p1 = __builtin_amdgcn_mfma_f32_32x32x16_bf16(b1, qr[d0], p1, 0, 0, 0); }
	v_mfma_f32_32x32x16_bf16 v[80:95], v[146:149], v[112:115], v[80:95]
	s_waitcnt lgkmcnt(0)
	v_mfma_f32_32x32x16_bf16 v[64:79], v[150:153], v[112:115], v[64:79]
	ds_read_b128 v[146:149], v229 offset:49408
	ds_read_b128 v[150:153], v229 offset:62208
	s_waitcnt lgkmcnt(1)
	v_mfma_f32_32x32x16_bf16 v[80:95], v[146:149], v[108:111], v[80:95]
	s_waitcnt lgkmcnt(0)
	v_mfma_f32_32x32x16_bf16 v[64:79], v[150:153], v[108:111], v[64:79]
	ds_read_b128 v[146:149], v229 offset:49440
	ds_read_b128 v[150:153], v229 offset:62240
	s_waitcnt lgkmcnt(1)
	v_mfma_f32_32x32x16_bf16 v[80:95], v[146:149], v[104:107], v[80:95]
	s_waitcnt lgkmcnt(0)
	v_mfma_f32_32x32x16_bf16 v[64:79], v[150:153], v[104:107], v[64:79]
	ds_read_b128 v[146:149], v229 offset:49472
	ds_read_b128 v[150:153], v229 offset:62272
	s_waitcnt lgkmcnt(1)
	v_mfma_f32_32x32x16_bf16 v[80:95], v[146:149], v[100:103], v[80:95]
	s_waitcnt lgkmcnt(0)
	v_mfma_f32_32x32x16_bf16 v[64:79], v[150:153], v[100:103], v[64:79]
	ds_read_b128 v[146:149], v229 offset:49504
	ds_read_b128 v[150:153], v229 offset:62304
	s_waitcnt lgkmcnt(1)
	v_mfma_f32_32x32x16_bf16 v[80:95], v[146:149], v[96:99], v[80:95]
	v_exp_f32_e32 v146, v158
	v_exp_f32_e32 v147, v218
	v_exp_f32_e32 v148, v184
	v_exp_f32_e32 v149, v219
	v_exp_f32_e32 v218, v221
	v_exp_f32_e32 v219, v222
	v_exp_f32_e32 v221, v224
	s_waitcnt lgkmcnt(0)
	v_mfma_f32_32x32x16_bf16 v[64:79], v[150:153], v[96:99], v[64:79]
	v_add_f32_e32 v150, 0, v155
	v_add_f32_e32 v150, v156, v150
	v_add_f32_e32 v150, v157, v150
	v_add_f32_e32 v150, v159, v150
	v_add_f32_e32 v150, v160, v150
	v_add_f32_e32 v150, v161, v150
	v_add_f32_e32 v150, v180, v150
	v_add_f32_e32 v150, v189, v150
	v_add_f32_e32 v150, v191, v150
	v_cvt_pk_bf16_f32 v160, v160, v161
	v_cvt_pk_bf16_f32 v161, v180, v189
	v_max_f32_e32 v180, v81, v81
	v_max_f32_e32 v189, v80, v80
	v_add_f32_e32 v150, v198, v150
	v_max_f32_e32 v180, v189, v180
	v_add_f32_e32 v150, v199, v150
	v_max3_f32 v180, v180, v82, v83
	v_add_f32_e32 v150, v200, v150
	v_max3_f32 v180, v180, v84, v85
	v_add_f32_e32 v150, v201, v150
	v_max3_f32 v180, v180, v86, v87
	v_add_f32_e32 v150, v214, v150
	v_max3_f32 v180, v180, v88, v89
	v_add_f32_e32 v150, v215, v150
	v_max3_f32 v180, v180, v90, v91
	v_add_f32_e32 v150, v216, v150
	v_max3_f32 v180, v180, v92, v93
	v_exp_f32_e32 v152, v185
	v_add_f32_e32 v150, v146, v150
	v_max3_f32 v180, v180, v94, v95
	v_exp_f32_e32 v153, v220
	v_add_f32_e32 v150, v147, v150
	v_max3_f32 v180, v180, v64, v65
	v_add_f32_e32 v150, v148, v150
	v_max3_f32 v180, v180, v66, v67
	v_add_f32_e32 v150, v149, v150
	v_max3_f32 v180, v180, v68, v69
	v_add_f32_e32 v150, v152, v150
	v_max3_f32 v180, v180, v70, v71
	v_exp_f32_e32 v220, v223
	v_add_f32_e32 v150, v153, v150
	v_max3_f32 v180, v180, v72, v73
	v_add_f32_e32 v150, v217, v150
	v_max3_f32 v180, v180, v74, v75
	v_exp_f32_e32 v222, v225
	v_add_f32_e32 v150, v218, v150
	v_max3_f32 v180, v180, v76, v77
	v_exp_f32_e32 v223, v226
	v_add_f32_e32 v150, v219, v150
	v_max3_f32 v180, v180, v78, v79
	v_exp_f32_e32 v224, v227
	v_add_f32_e32 v150, v220, v150
	v_mov_b32_e32 v189, v180
	v_exp_f32_e32 v225, v228
	v_add_f32_e32 v150, v221, v150
	v_permlane32_swap_b32_e32 v180, v189
	v_exp_f32_e32 v226, v154
	v_add_f32_e32 v150, v222, v150
	v_max_f32_e32 v189, v189, v189
	v_max_f32_e32 v180, v180, v180
	v_add_f32_e32 v150, v223, v150
	v_max_f32_e32 v180, v180, v189
	v_add_f32_e32 v150, v224, v150
	v_sub_f32_e32 v189, v180, v178
	v_add_f32_e32 v150, v225, v150
	v_cmp_ge_f32_e32 vcc, s56, v189
	v_max_f32_e32 v189, v178, v178
	v_add_f32_e32 v184, v226, v150
	v_max_f32_e32 v189, v189, v180
	v_mov_b32_e32 v185, v184
	s_cmp_eq_u64 vcc, exec
	v_sub_f32_e32 v180, v178, v189
	v_permlane32_swap_b32_e32 v184, v185
	s_cselect_b64 s[8:9], -1, 0
	v_mul_f32_e32 v180, 0x3dd53b94, v180
	v_cvt_pk_bf16_f32 v158, v155, v156
	v_cvt_pk_bf16_f32 v159, v157, v159
	v_cvt_pk_bf16_f32 v154, v191, v198
	v_cvt_pk_bf16_f32 v155, v199, v200
	v_cvt_pk_bf16_f32 v156, v201, v214
	v_cvt_pk_bf16_f32 v157, v215, v216
	v_cvt_pk_bf16_f32 v150, v146, v147
	v_cvt_pk_bf16_f32 v151, v148, v149
	v_cvt_pk_bf16_f32 v152, v152, v153
	v_cvt_pk_bf16_f32 v153, v217, v218
	v_cvt_pk_bf16_f32 v146, v219, v220
	v_cvt_pk_bf16_f32 v147, v221, v222
	v_cvt_pk_bf16_f32 v148, v223, v224
	v_cvt_pk_bf16_f32 v149, v225, v226
	s_add_i32 s10, s13, 0xffff8000
	s_add_i32 s11, s12, 0x18000
	s_mov_b32 s38, s30
	s_mov_b32 s39, s31
	buffer_load_dwordx4 v[198:201], v170, s[28:31], s10 offen
	buffer_load_dwordx4 v[214:217], v170, s[28:31], s13 offen
	buffer_load_dwordx4 v[218:221], v171, s[36:39], s11 offen
	buffer_load_dwordx4 v[222:225], v176, s[36:39], s11 offen
	buffer_load_dwordx4 v[226:229], v177, s[36:39], s11 offen
	v_exp_f32_e32 v180, v180
	v_lshl_add_u32 v191, s14, 14, v168
	ds_read_b64_tr_b16 v[230:231], v191 offset:0
	ds_read_b64_tr_b16 v[232:233], v191 offset:0x800
	ds_read_b64_tr_b16 v[234:235], v191 offset:0x1000
	ds_read_b64_tr_b16 v[236:237], v191 offset:0x1800
	ds_read_b64_tr_b16 v[238:239], v191 offset:0x2000
	ds_read_b64_tr_b16 v[240:241], v191 offset:0x2800
	ds_read_b64_tr_b16 v[242:243], v191 offset:0x3000
	ds_read_b64_tr_b16 v[244:245], v191 offset:0x3800
	s_waitcnt lgkmcnt(6)
; #define SBAR() __builtin_amdgcn_sched_barrier(0)
; template <int D0> __device__ __forceinline__ void pv_one_sm(f32x16& od, int vb, bf16x8 pa0, bf16x8 pa1, bf16x8 pa2, bf16x8 pa3, f32x16& q0, f32x16& q1, const float C, const float mnC) {
;   const s16x4 l0 = tr_read<v_rd_off(D0, 0, 0)>(vb), h0 = tr_read<v_rd_off(D0, 0, 1)>(vb), l1 = tr_read<v_rd_off(D0, 1, 0)>(vb), h1 = tr_read<v_rd_off(D0, 1, 1)>(vb);
;   const s16x4 l2 = tr_read<v_rd_off(D0, 2, 0)>(vb), h2 = tr_read<v_rd_off(D0, 2, 1)>(vb), l3 = tr_read<v_rd_off(D0, 3, 0)>(vb), h3 = tr_read<v_rd_off(D0, 3, 1)>(vb);
;   asm volatile("s_waitcnt lgkmcnt(0)" ::: "memory"); SBAR();
;     ...
;   od = __builtin_amdgcn_mfma_f32_32x32x16_bf16(pa0, PK(l0, h0), od, 0, 0, 0);
;   od = __builtin_amdgcn_mfma_f32_32x32x16_bf16(pa1, PK(l1, h1), od, 0, 0, 0);
;   od = __builtin_amdgcn_mfma_f32_32x32x16_bf16(pa2, PK(l2, h2), od, 0, 0, 0);
;   od = __builtin_amdgcn_mfma_f32_32x32x16_bf16(pa3, PK(l3, h3), od, 0, 0, 0);
	s_nop 0
	v_mfma_f32_32x32x16_bf16 v[0:15], v[158:161], v[230:233], v[0:15]
	ds_read_b64_tr_b16 v[230:231], v191 offset:0x200
	ds_read_b64_tr_b16 v[232:233], v191 offset:0xa00
	s_waitcnt lgkmcnt(6)
	v_mfma_f32_32x32x16_bf16 v[0:15], v[154:157], v[234:237], v[0:15]
	ds_read_b64_tr_b16 v[234:235], v191 offset:0x1200
	ds_read_b64_tr_b16 v[236:237], v191 offset:0x1a00
	s_waitcnt lgkmcnt(6)
	v_mfma_f32_32x32x16_bf16 v[0:15], v[150:153], v[238:241], v[0:15]
	ds_read_b64_tr_b16 v[238:239], v191 offset:0x2200
	ds_read_b64_tr_b16 v[240:241], v191 offset:0x2a00
	s_waitcnt lgkmcnt(6)
	v_mfma_f32_32x32x16_bf16 v[0:15], v[146:149], v[242:245], v[0:15]
	ds_read_b64_tr_b16 v[242:243], v191 offset:0x3200
	ds_read_b64_tr_b16 v[244:245], v191 offset:0x3a00
	s_waitcnt lgkmcnt(6)
	v_mfma_f32_32x32x16_bf16 v[48:63], v[158:161], v[230:233], v[48:63]
	ds_read_b64_tr_b16 v[230:231], v191 offset:0x400
	ds_read_b64_tr_b16 v[232:233], v191 offset:0xc00
	s_waitcnt lgkmcnt(6)
	v_mfma_f32_32x32x16_bf16 v[48:63], v[154:157], v[234:237], v[48:63]
	ds_read_b64_tr_b16 v[234:235], v191 offset:0x1400
	ds_read_b64_tr_b16 v[236:237], v191 offset:0x1c00
	s_waitcnt lgkmcnt(6)
	v_mfma_f32_32x32x16_bf16 v[48:63], v[150:153], v[238:241], v[48:63]
	ds_read_b64_tr_b16 v[238:239], v191 offset:0x2400
	ds_read_b64_tr_b16 v[240:241], v191 offset:0x2c00
	s_waitcnt lgkmcnt(6)
	v_mfma_f32_32x32x16_bf16 v[48:63], v[146:149], v[242:245], v[48:63]
	ds_read_b64_tr_b16 v[242:243], v191 offset:0x3400
	ds_read_b64_tr_b16 v[244:245], v191 offset:0x3c00
	s_waitcnt lgkmcnt(6)
	v_mfma_f32_32x32x16_bf16 v[32:47], v[158:161], v[230:233], v[32:47]
	ds_read_b64_tr_b16 v[230:231], v191 offset:0x600
	ds_read_b64_tr_b16 v[232:233], v191 offset:0xe00
	s_waitcnt lgkmcnt(6)
	v_mfma_f32_32x32x16_bf16 v[32:47], v[154:157], v[234:237], v[32:47]
	ds_read_b64_tr_b16 v[234:235], v191 offset:0x1600
	ds_read_b64_tr_b16 v[236:237], v191 offset:0x1e00
	s_waitcnt lgkmcnt(6)
	v_mfma_f32_32x32x16_bf16 v[32:47], v[150:153], v[238:241], v[32:47]
	ds_read_b64_tr_b16 v[238:239], v191 offset:0x2600
	ds_read_b64_tr_b16 v[240:241], v191 offset:0x2e00
	s_waitcnt lgkmcnt(6)
	v_mfma_f32_32x32x16_bf16 v[32:47], v[146:149], v[242:245], v[32:47]
	ds_read_b64_tr_b16 v[242:243], v191 offset:0x3600
	ds_read_b64_tr_b16 v[244:245], v191 offset:0x3e00
	s_waitcnt lgkmcnt(0)
	v_mfma_f32_32x32x16_bf16 v[16:31], v[158:161], v[230:233], v[16:31]
	s_waitcnt vmcnt(0)
	v_cndmask_b32_e64 v180, v180, 1.0, s[8:9]
	v_cmp_gt_f32_e32 vcc, 1.0, v180
	v_mfma_f32_32x32x16_bf16 v[16:31], v[154:157], v[234:237], v[16:31]
	v_add_u32_e32 v154, s16, v175
	s_mul_i32 s16, s44, 0x6400
	s_waitcnt vmcnt(4)
	ds_write_b128 v154, v[198:201]
	s_waitcnt vmcnt(3)
	ds_write_b128 v154, v[214:217] offset:8192
	v_mfma_f32_32x32x16_bf16 v[16:31], v[150:153], v[238:241], v[16:31]
	v_add_u32_e32 v150, s16, v173
	s_waitcnt vmcnt(2)
	ds_write_b128 v150, v[218:221] offset:49152
	s_waitcnt vmcnt(1)
	ds_write_b128 v150, v[222:225] offset:49280
	s_waitcnt vmcnt(0)
	ds_write_b128 v150, v[226:229] offset:49408
	v_mfma_f32_32x32x16_bf16 v[16:31], v[146:149], v[242:245], v[16:31]
	s_cbranch_vccz .LBB0_2547
	s_and_saveexec_b64 s[10:11], s[6:7]
	ds_write_b32 v166, v180 offset:128
	s_or_b64 exec, exec, s[10:11]
	s_waitcnt lgkmcnt(0)
	v_add_u32_e32 v158, v165, v162
	ds_read_b128 v[146:149], v158 offset:224
	ds_read_b128 v[150:153], v158 offset:192
	ds_read_b128 v[154:157], v158 offset:160
	ds_read_b128 v[158:161], v158 offset:128
	s_waitcnt lgkmcnt(3)
	v_pk_mul_f32 v[12:13], v[12:13], v[146:147]
	s_waitcnt lgkmcnt(2)
	v_pk_mul_f32 v[8:9], v[8:9], v[150:151]
	s_waitcnt lgkmcnt(1)
	v_pk_mul_f32 v[4:5], v[4:5], v[154:155]
	v_pk_mul_f32 v[14:15], v[14:15], v[148:149]
	v_pk_mul_f32 v[10:11], v[10:11], v[152:153]
	v_pk_mul_f32 v[6:7], v[6:7], v[156:157]
	s_waitcnt lgkmcnt(0)
	v_pk_mul_f32 v[2:3], v[2:3], v[160:161]
	v_pk_mul_f32 v[0:1], v[0:1], v[158:159]
	v_pk_mul_f32 v[60:61], v[60:61], v[146:147]
	v_pk_mul_f32 v[56:57], v[56:57], v[150:151]
	v_pk_mul_f32 v[52:53], v[52:53], v[154:155]
	v_pk_mul_f32 v[62:63], v[62:63], v[148:149]
	v_pk_mul_f32 v[58:59], v[58:59], v[152:153]
	v_pk_mul_f32 v[54:55], v[54:55], v[156:157]
	v_pk_mul_f32 v[50:51], v[50:51], v[160:161]
	v_pk_mul_f32 v[48:49], v[48:49], v[158:159]
	v_pk_mul_f32 v[44:45], v[44:45], v[146:147]
	v_pk_mul_f32 v[40:41], v[40:41], v[150:151]
	v_pk_mul_f32 v[36:37], v[36:37], v[154:155]
	v_pk_mul_f32 v[46:47], v[46:47], v[148:149]
	v_pk_mul_f32 v[42:43], v[42:43], v[152:153]
	v_pk_mul_f32 v[38:39], v[38:39], v[156:157]
	v_pk_mul_f32 v[34:35], v[34:35], v[160:161]
	v_pk_mul_f32 v[32:33], v[32:33], v[158:159]
	v_pk_mul_f32 v[28:29], v[28:29], v[146:147]
	v_pk_mul_f32 v[24:25], v[24:25], v[150:151]
	v_pk_mul_f32 v[20:21], v[20:21], v[154:155]
	v_pk_mul_f32 v[30:31], v[30:31], v[148:149]
	v_pk_mul_f32 v[26:27], v[26:27], v[152:153]
	v_pk_mul_f32 v[22:23], v[22:23], v[156:157]
	v_pk_mul_f32 v[18:19], v[18:19], v[160:161]
	v_pk_mul_f32 v[16:17], v[16:17], v[158:159]
